# P1 h0 rows: chunk 1..3 modulation vector loads of both rows hoisted to the item top (rows r, r+4 share the modulation row), on top of the current best
# speedup vs baseline: 1.0154x; 1.0076x over previous
; DEVI void h0_rows(const P& p, int it) {
;     const int lane = threadIdx.x & 63, w = threadIdx.x >> 6;
;     int r[2], b[2], t[2]; const float* src[2]; const float* mod[2];
; #pragma unroll
;     for (int q = 0; q < 2; ++q) {
;         r[q] = it * 8 + w + 4 * q; b[q] = r[q] / TPB; t[q] = r[q] - b[q] * TPB;
;         src[q] = t[q] < CTX ? p.ctx + (size_t)(b[q] * CTX + t[q]) * 1024 : p.x + (size_t)(b[q] * SEQ + t[q] - CTX) * 1024;
;         mod[q] = (const float*)(p.ws + OFF_MODS) + (size_t)(t[q] < CTX ? 8 : b[q]) * 3072;
;     }
;     f32x4 v[2][4];
;     float ss[2] = {0.f, 0.f};
; #pragma unroll
;     for (int q = 0; q < 2; ++q)
; #pragma unroll
;         for (int i = 0; i < 4; ++i) v[q][i] = *(const f32x4*)(src[q] + (i * 64 + lane) * 4);
; #pragma unroll
;     for (int q = 0; q < 2; ++q) {
; #pragma unroll
;         for (int i = 0; i < 4; ++i) ss[q] += sumsq4(v[q][i]);
;         ss[q] = wave_sum(ss[q]);
;     }
.LBB0_84:
	s_cmpk_gt_i32 s61, 0xff
	s_mov_b64 s[0:1], -1
	s_cbranch_scc0 .LBB0_108
	s_cmpk_gt_u32 s61, 0x9bf
	s_cbranch_scc0 .LBB0_119
	s_cmpk_gt_u32 s61, 0xebf
	s_cbranch_scc0 .LBB0_111
	s_cmpk_lg_i32 s61, 0xec0
	s_cbranch_scc0 .LBB0_97
	v_lshl_add_u32 v71, s61, 3, v49
	v_mul_u32_u24_e32 v0, 0xf0f1, v71
	v_lshrrev_b32_e32 v32, 28, v0
	v_mad_i32_i24 v0, v32, s31, v71
	v_cmp_gt_i32_e64 s[6:7], s24, v0
	v_cmp_lt_i32_e32 vcc, s30, v0
	v_mov_b64_e32 v[2:3], s[56:57]
	s_and_saveexec_b64 s[0:1], vcc
	s_xor_b64 s[0:1], exec, s[0:1]
	v_lshlrev_b32_e32 v1, 12, v32
	v_add3_u32 v44, v1, v0, s29
	v_mov_b64_e32 v[2:3], s[52:53]
	v_mov_b64_e32 v[6:7], v[44:45]
	s_andn2_saveexec_b64 s[0:1], s[0:1]
	v_lshl_add_u32 v6, v32, 8, v0
	v_ashrrev_i32_e32 v7, 31, v6
	s_or_b64 exec, exec, s[0:1]
	v_add_u32_e32 v77, 4, v71
	v_mul_u32_u24_e32 v0, 0xf0f1, v77
	v_lshrrev_b32_e32 v33, 28, v0
	v_mad_i32_i24 v8, v33, s31, v77
	v_cmp_gt_i32_e32 vcc, s24, v8
	v_cmp_lt_i32_e64 s[8:9], s30, v8
	v_mov_b64_e32 v[0:1], s[56:57]
	s_and_saveexec_b64 s[0:1], s[8:9]
	s_xor_b64 s[0:1], exec, s[0:1]
	v_lshlrev_b32_e32 v0, 12, v33
	v_add3_u32 v44, v0, v8, s29
	v_mov_b64_e32 v[0:1], s[52:53]
	v_mov_b64_e32 v[4:5], v[44:45]
	s_andn2_saveexec_b64 s[0:1], s[0:1]
	v_lshl_add_u32 v4, v33, 8, v8
	v_ashrrev_i32_e32 v5, 31, v4
	s_or_b64 exec, exec, s[0:1]
	v_lshlrev_b64 v[6:7], 12, v[6:7]
	v_lshl_add_u64 v[2:3], v[2:3], 0, v[6:7]
	v_mov_b32_e32 v69, v45
	v_lshl_add_u64 v[2:3], v[2:3], 0, v[68:69]
	global_load_dwordx4 v[28:31], v[2:3], off
	global_load_dwordx4 v[24:27], v[2:3], off offset:1024
	global_load_dwordx4 v[20:23], v[2:3], off offset:2048
	global_load_dwordx4 v[16:19], v[2:3], off offset:3072
	v_lshlrev_b64 v[2:3], 12, v[4:5]
	v_lshl_add_u64 v[0:1], v[0:1], 0, v[2:3]
	v_lshl_add_u64 v[0:1], v[0:1], 0, v[68:69]
	global_load_dwordx4 v[12:15], v[0:1], off
	global_load_dwordx4 v[8:11], v[0:1], off offset:1024
	global_load_dwordx4 v[4:7], v[0:1], off offset:2048
	s_nop 0
	global_load_dwordx4 v[0:3], v[0:1], off offset:3072
	v_mul_u32_u24_e32 v36, 0xc00, v32
	v_cndmask_b32_e64 v36, v36, v149, s[6:7]
	v_and_b32_e32 v37, 64, v151
	v_lshlrev_b32_e32 v44, 2, v36
	v_xor_b32_e32 v38, 32, v151
	v_add_u32_e32 v79, 64, v37
	v_lshl_add_u64 v[36:37], s[18:19], 0, v[44:45]
	v_cmp_lt_i32_e64 s[6:7], v38, v79
	v_lshl_add_u64 v[86:87], v[36:37], 0, s[22:23]
	v_lshl_add_u64 v[88:89], v[36:37], 0, v[68:69]
	v_cndmask_b32_e64 v38, v151, v38, s[6:7]
	v_lshl_add_u64 v[40:41], v[86:87], 0, v[68:69]
	v_mul_u32_u24_e32 v73, 0xc00, v33
	global_load_dwordx4 v[32:35], v[46:47], off
	v_lshlrev_b32_e32 v44, 2, v38
	global_load_dwordx4 v[36:39], v[88:89], off
	s_nop 0
	global_load_dwordx4 v[40:43], v[40:41], off
	v_lshl_add_u64 v[214:215], v[86:87], 0, v[68:69]
	global_load_dwordx4 v[190:193], v[46:47], off offset:1024
	global_load_dwordx4 v[202:205], v[214:215], off offset:1024
	global_load_dwordx4 v[218:221], v[88:89], off offset:1024
	global_load_dwordx4 v[194:197], v[46:47], off offset:2048
	global_load_dwordx4 v[206:209], v[214:215], off offset:2048
	global_load_dwordx4 v[222:225], v[88:89], off offset:2048
	global_load_dwordx4 v[198:201], v[46:47], off offset:3072
	global_load_dwordx4 v[210:213], v[214:215], off offset:3072
	global_load_dwordx4 v[226:229], v[88:89], off offset:3072
	v_xor_b32_e32 v75, 16, v151
	v_cmp_lt_i32_e64 s[6:7], v75, v79
	v_cndmask_b32_e32 v73, v73, v149, vcc
	s_mov_b32 s0, 0x3a800000
	v_cndmask_b32_e64 v75, v151, v75, s[6:7]
	v_lshlrev_b32_e32 v75, 2, v75
	s_waitcnt vmcnt(19)
	v_mov_b32_e32 v92, v29
	s_waitcnt vmcnt(18)
	v_mov_b32_e32 v93, v25
	s_waitcnt vmcnt(17)
	v_mov_b32_e32 v100, v21
	s_waitcnt vmcnt(16)
	v_mov_b32_e32 v101, v17
	s_waitcnt vmcnt(15)
	v_mov_b32_e32 v164, v13
	s_waitcnt vmcnt(14)
	v_mov_b32_e32 v165, v9
	v_mov_b32_e32 v90, v28
	v_mov_b32_e32 v91, v24
	v_mov_b32_e32 v98, v20
	v_mov_b32_e32 v99, v16
	v_mov_b32_e32 v106, v12
	v_mov_b32_e32 v107, v8
	s_waitcnt vmcnt(13)
	v_mov_b32_e32 v184, v5
	s_waitcnt vmcnt(12)
	v_mov_b32_e32 v185, v1
	v_pk_mul_f32 v[92:93], v[92:93], v[92:93]
	v_pk_mul_f32 v[100:101], v[100:101], v[100:101]
	v_pk_mul_f32 v[164:165], v[164:165], v[164:165]
	v_mov_b32_e32 v94, v30
	v_mov_b32_e32 v95, v26
	v_mov_b32_e32 v166, v14
	v_mov_b32_e32 v167, v10
	v_mov_b32_e32 v170, v4
	v_mov_b32_e32 v171, v0
	v_pk_mul_f32 v[184:185], v[184:185], v[184:185]
	v_pk_fma_f32 v[90:91], v[90:91], v[90:91], v[92:93]
	v_pk_fma_f32 v[92:93], v[98:99], v[98:99], v[100:101]
	v_pk_fma_f32 v[98:99], v[106:107], v[106:107], v[164:165]
	v_mov_b32_e32 v96, v31
	v_mov_b32_e32 v97, v27
	v_mov_b32_e32 v102, v22
	v_mov_b32_e32 v103, v18
	v_mov_b32_e32 v168, v15
	v_mov_b32_e32 v169, v11
	v_mov_b32_e32 v186, v6
	v_mov_b32_e32 v187, v2
	v_pk_fma_f32 v[100:101], v[170:171], v[170:171], v[184:185]
	v_pk_fma_f32 v[90:91], v[94:95], v[94:95], v[90:91]
	v_pk_fma_f32 v[94:95], v[166:167], v[166:167], v[98:99]
	v_mov_b32_e32 v104, v23
	v_mov_b32_e32 v105, v19
	v_mov_b32_e32 v188, v7
	v_mov_b32_e32 v189, v3
	v_pk_fma_f32 v[92:93], v[102:103], v[102:103], v[92:93]
	v_pk_fma_f32 v[98:99], v[186:187], v[186:187], v[100:101]
	v_pk_fma_f32 v[90:91], v[96:97], v[96:97], v[90:91]
	v_pk_fma_f32 v[94:95], v[168:169], v[168:169], v[94:95]
	v_pk_fma_f32 v[92:93], v[104:105], v[104:105], v[92:93]
	v_pk_fma_f32 v[96:97], v[188:189], v[188:189], v[98:99]
	v_mov_b32_e32 v98, v94
	v_mov_b32_e32 v99, v90
	v_mov_b32_e32 v90, v95
	v_mov_b32_e32 v94, v96
	v_mov_b32_e32 v95, v92
	v_pk_add_f32 v[90:91], v[98:99], v[90:91]
	v_mov_b32_e32 v92, v97
	v_pk_add_f32 v[90:91], v[90:91], v[94:95]
	s_waitcnt vmcnt(0)
; DEVI unsigned pk2(float lo, float hi) { f32x2 v = {lo, hi}; bf16x2_t b = __builtin_convertvector(v, bf16x2_t); return __builtin_bit_cast(unsigned, b); }
; DEVI void h0_rows(const P& p, int it) {
;     ...
;     for (int q = 0; q < 2; ++q) {
; #pragma unroll
;         for (int i = 0; i < 4; ++i) ss[q] += sumsq4(v[q][i]);
;         ss[q] = wave_sum(ss[q]);
;     }
; #pragma unroll
;     for (int q = 0; q < 2; ++q) {
;         const float rstd = rsqrtf(ss[q] * (1.0f / 1024.0f) + 1e-6f);
;         bf16_t* hb = (bf16_t*)(p.ws + OFF_A) + (size_t)r[q] * 1024;
; #pragma unroll
;         for (int i = 0; i < 4; ++i) {
;             const int col = (i * 64 + lane) * 4;
;             const f32x4 g = *(const f32x4*)(p.g_pre0 + col), sh = *(const f32x4*)(mod[q] + col), sc = *(const f32x4*)(mod[q] + 1024 + col);
;             const f32x4 h = (v[q][i] * rstd * g) * (sc + 1.0f) + sh;
;             uint2 o; o.x = pk2(h[0], h[1]); o.y = pk2(h[2], h[3]);
;             *(uint2*)(hb + col) = o;
;         }
;     }
	v_pk_add_f32 v[96:97], v[42:43], 1.0 op_sel_hi:[1,0]
	v_pk_add_f32 v[90:91], v[90:91], v[92:93]
	ds_bpermute_b32 v93, v44, v91
	ds_bpermute_b32 v92, v44, v90
	v_xor_b32_e32 v44, 8, v151
	v_cmp_lt_i32_e32 vcc, v44, v79
	v_pk_add_f32 v[40:41], v[40:41], 1.0 op_sel_hi:[1,0]
	s_waitcnt lgkmcnt(0)
	v_pk_add_f32 v[90:91], v[90:91], v[92:93]
	ds_bpermute_b32 v93, v75, v91
	ds_bpermute_b32 v92, v75, v90
	v_cndmask_b32_e32 v44, v151, v44, vcc
	v_lshlrev_b32_e32 v44, 2, v44
	v_mov_b32_e32 v75, v45
	s_waitcnt lgkmcnt(0)
	v_pk_add_f32 v[90:91], v[90:91], v[92:93]
	ds_bpermute_b32 v93, v44, v91
	ds_bpermute_b32 v92, v44, v90
	v_xor_b32_e32 v44, 4, v151
	v_cmp_lt_i32_e32 vcc, v44, v79
	s_waitcnt lgkmcnt(0)
	v_pk_add_f32 v[90:91], v[90:91], v[92:93]
	v_cndmask_b32_e32 v44, v151, v44, vcc
	v_lshlrev_b32_e32 v44, 2, v44
	ds_bpermute_b32 v93, v44, v91
	ds_bpermute_b32 v92, v44, v90
	v_xor_b32_e32 v44, 2, v151
	v_cmp_lt_i32_e32 vcc, v44, v79
	s_waitcnt lgkmcnt(0)
	v_pk_add_f32 v[90:91], v[90:91], v[92:93]
	v_cndmask_b32_e32 v44, v151, v44, vcc
	v_lshlrev_b32_e32 v44, 2, v44
	ds_bpermute_b32 v93, v44, v91
	ds_bpermute_b32 v92, v44, v90
	v_xor_b32_e32 v44, 1, v151
	v_cmp_lt_i32_e32 vcc, v44, v79
	s_waitcnt lgkmcnt(0)
	v_pk_add_f32 v[92:93], v[90:91], v[92:93]
	v_cndmask_b32_e32 v44, v151, v44, vcc
	v_lshlrev_b32_e32 v44, 2, v44
	ds_bpermute_b32 v95, v44, v93
	ds_bpermute_b32 v94, v44, v92
	v_lshlrev_b32_e32 v44, 2, v73
	v_lshl_add_u64 v[90:91], s[18:19], 0, v[44:45]
	v_lshlrev_b32_e32 v44, 11, v71
	v_mov_b32_e32 v73, v45
	s_waitcnt lgkmcnt(0)
	v_pk_add_f32 v[42:43], v[92:93], v[94:95]
	v_lshl_add_u64 v[92:93], v[62:63], 0, v[44:45]
	v_pk_fma_f32 v[42:43], v[42:43], s[0:1], v[84:85] op_sel_hi:[1,0,0]
	s_mov_b64 s[0:1], 0
	v_mul_f32_e32 v71, 0x4b800000, v43
	v_cmp_gt_f32_e32 vcc, s34, v43
	s_nop 1
	v_cndmask_b32_e32 v43, v43, v71, vcc
	v_rsq_f32_e32 v43, v43
	v_mov_b32_e32 v71, v45
	v_mul_f32_e32 v44, 0x45800000, v43
	v_cndmask_b32_e32 v44, v43, v44, vcc
	v_pk_mul_f32 v[30:31], v[30:31], v[44:45] op_sel_hi:[1,0]
	v_pk_mul_f32 v[28:29], v[28:29], v[44:45] op_sel_hi:[1,0]
	v_pk_mul_f32 v[30:31], v[34:35], v[30:31]
	v_pk_mul_f32 v[28:29], v[32:33], v[28:29]
	v_pk_fma_f32 v[30:31], v[96:97], v[30:31], v[38:39]
	v_pk_fma_f32 v[28:29], v[40:41], v[28:29], v[36:37]
	v_lshl_add_u64 v[32:33], v[86:87], 0, v[70:71]
	v_cvt_pk_bf16_f32 v28, v28, v29
	v_cvt_pk_bf16_f32 v29, v30, v31
	global_store_dwordx2 v[92:93], v[28:29], off
	s_nop 0
	s_nop 0
	v_pk_mul_f32 v[26:27], v[26:27], v[44:45] op_sel_hi:[1,0]
	v_pk_mul_f32 v[24:25], v[24:25], v[44:45] op_sel_hi:[1,0]
	v_pk_mul_f32 v[22:23], v[22:23], v[44:45] op_sel_hi:[1,0]
	v_pk_mul_f32 v[20:21], v[20:21], v[44:45] op_sel_hi:[1,0]
	v_pk_mul_f32 v[18:19], v[18:19], v[44:45] op_sel_hi:[1,0]
	v_pk_mul_f32 v[16:17], v[16:17], v[44:45] op_sel_hi:[1,0]
	v_cmp_gt_f32_e32 vcc, s34, v42
	v_lshlrev_b32_e32 v44, 11, v77
	v_pk_mul_f32 v[24:25], v[190:191], v[24:25]
	v_pk_mul_f32 v[26:27], v[192:193], v[26:27]
	v_pk_add_f32 v[28:29], v[204:205], 1.0 op_sel_hi:[1,0]
	v_pk_add_f32 v[30:31], v[202:203], 1.0 op_sel_hi:[1,0]
	v_pk_fma_f32 v[26:27], v[26:27], v[28:29], v[220:221]
	v_pk_fma_f32 v[24:25], v[24:25], v[30:31], v[218:219]
	v_lshl_add_u64 v[28:29], v[86:87], 0, v[72:73]
	v_cvt_pk_bf16_f32 v24, v24, v25
	v_cvt_pk_bf16_f32 v25, v26, v27
	global_store_dwordx2 v[92:93], v[24:25], off offset:512
	s_nop 0
	s_nop 0
	v_pk_mul_f32 v[20:21], v[20:21], v[194:195]
	v_pk_mul_f32 v[22:23], v[22:23], v[196:197]
	v_pk_add_f32 v[24:25], v[208:209], 1.0 op_sel_hi:[1,0]
	v_pk_add_f32 v[26:27], v[206:207], 1.0 op_sel_hi:[1,0]
	v_pk_fma_f32 v[22:23], v[22:23], v[24:25], v[224:225]
	v_pk_fma_f32 v[20:21], v[20:21], v[26:27], v[222:223]
	v_lshl_add_u64 v[24:25], v[86:87], 0, v[74:75]
	v_cvt_pk_bf16_f32 v20, v20, v21
	v_cvt_pk_bf16_f32 v21, v22, v23
	global_store_dwordx2 v[92:93], v[20:21], off offset:1024
	s_nop 0
	s_nop 0
	v_lshl_add_u64 v[32:33], v[90:91], 0, s[22:23]
	v_pk_mul_f32 v[16:17], v[16:17], v[198:199]
	v_pk_mul_f32 v[18:19], v[18:19], v[200:201]
	v_pk_add_f32 v[20:21], v[212:213], 1.0 op_sel_hi:[1,0]
	v_pk_add_f32 v[22:23], v[210:211], 1.0 op_sel_hi:[1,0]
	v_pk_fma_f32 v[18:19], v[18:19], v[20:21], v[228:229]
	v_pk_fma_f32 v[16:17], v[16:17], v[22:23], v[226:227]
	v_lshl_add_u64 v[20:21], v[32:33], 0, v[68:69]
	v_cvt_pk_bf16_f32 v16, v16, v17
	v_cvt_pk_bf16_f32 v17, v18, v19
	global_store_dwordx2 v[92:93], v[16:17], off offset:1536
	global_load_dwordx4 v[16:19], v[46:47], off
	v_lshl_add_u64 v[28:29], v[90:91], 0, v[68:69]
	global_load_dwordx4 v[20:23], v[20:21], off
	v_mul_f32_e32 v30, 0x4b800000, v42
	global_load_dwordx4 v[24:27], v[28:29], off
	v_cndmask_b32_e32 v30, v42, v30, vcc
	v_rsq_f32_e32 v34, v30
	v_lshl_add_u64 v[30:31], v[62:63], 0, v[44:45]
	v_mul_f32_e32 v35, 0x45800000, v34
	v_cndmask_b32_e32 v34, v34, v35, vcc
	v_pk_mul_f32 v[14:15], v[14:15], v[34:35] op_sel_hi:[1,0]
	v_pk_mul_f32 v[12:13], v[12:13], v[34:35] op_sel_hi:[1,0]
	v_pk_mul_f32 v[10:11], v[10:11], v[34:35] op_sel_hi:[1,0]
	v_pk_mul_f32 v[8:9], v[8:9], v[34:35] op_sel_hi:[1,0]
	v_pk_mul_f32 v[6:7], v[6:7], v[34:35] op_sel_hi:[1,0]
	v_pk_mul_f32 v[4:5], v[4:5], v[34:35] op_sel_hi:[1,0]
	v_pk_mul_f32 v[2:3], v[2:3], v[34:35] op_sel_hi:[1,0]
	v_pk_mul_f32 v[0:1], v[0:1], v[34:35] op_sel_hi:[1,0]
	s_waitcnt vmcnt(2)
; DEVI unsigned pk2(float lo, float hi) { f32x2 v = {lo, hi}; bf16x2_t b = __builtin_convertvector(v, bf16x2_t); return __builtin_bit_cast(unsigned, b); }
; DEVI void h0_rows(const P& p, int it) {
;     ...
;     for (int q = 0; q < 2; ++q) {
;         const float rstd = rsqrtf(ss[q] * (1.0f / 1024.0f) + 1e-6f);
;         bf16_t* hb = (bf16_t*)(p.ws + OFF_A) + (size_t)r[q] * 1024;
; #pragma unroll
;         for (int i = 0; i < 4; ++i) {
;             const int col = (i * 64 + lane) * 4;
;             const f32x4 g = *(const f32x4*)(p.g_pre0 + col), sh = *(const f32x4*)(mod[q] + col), sc = *(const f32x4*)(mod[q] + 1024 + col);
;             const f32x4 h = (v[q][i] * rstd * g) * (sc + 1.0f) + sh;
;             uint2 o; o.x = pk2(h[0], h[1]); o.y = pk2(h[2], h[3]);
;             *(uint2*)(hb + col) = o;
;         }
	v_pk_mul_f32 v[12:13], v[12:13], v[16:17]
	v_pk_mul_f32 v[14:15], v[14:15], v[18:19]
	s_waitcnt vmcnt(1)
	v_pk_add_f32 v[16:17], v[22:23], 1.0 op_sel_hi:[1,0]
	v_pk_add_f32 v[18:19], v[20:21], 1.0 op_sel_hi:[1,0]
	s_waitcnt vmcnt(0)
	v_pk_fma_f32 v[14:15], v[14:15], v[16:17], v[26:27]
	v_pk_fma_f32 v[12:13], v[12:13], v[18:19], v[24:25]
	v_lshl_add_u64 v[16:17], v[32:33], 0, v[70:71]
	v_cvt_pk_bf16_f32 v12, v12, v13
	v_cvt_pk_bf16_f32 v13, v14, v15
	global_store_dwordx2 v[30:31], v[12:13], off
	s_nop 0
	s_nop 0
	v_pk_mul_f32 v[8:9], v[8:9], v[190:191]
	v_pk_mul_f32 v[10:11], v[10:11], v[192:193]
	v_pk_add_f32 v[12:13], v[204:205], 1.0 op_sel_hi:[1,0]
	v_pk_add_f32 v[14:15], v[202:203], 1.0 op_sel_hi:[1,0]
	v_pk_fma_f32 v[10:11], v[10:11], v[12:13], v[220:221]
	v_pk_fma_f32 v[8:9], v[8:9], v[14:15], v[218:219]
	v_lshl_add_u64 v[12:13], v[32:33], 0, v[72:73]
	v_cvt_pk_bf16_f32 v8, v8, v9
	v_cvt_pk_bf16_f32 v9, v10, v11
	global_store_dwordx2 v[30:31], v[8:9], off offset:512
	s_nop 0
	s_nop 0
	v_pk_mul_f32 v[4:5], v[4:5], v[194:195]
	v_pk_mul_f32 v[6:7], v[6:7], v[196:197]
	v_pk_add_f32 v[8:9], v[208:209], 1.0 op_sel_hi:[1,0]
	v_pk_add_f32 v[10:11], v[206:207], 1.0 op_sel_hi:[1,0]
	v_pk_fma_f32 v[6:7], v[6:7], v[8:9], v[224:225]
	v_pk_fma_f32 v[4:5], v[4:5], v[10:11], v[222:223]
	v_lshl_add_u64 v[8:9], v[32:33], 0, v[74:75]
	v_cvt_pk_bf16_f32 v4, v4, v5
	v_cvt_pk_bf16_f32 v5, v6, v7
	global_store_dwordx2 v[30:31], v[4:5], off offset:1024
	s_nop 0
	s_nop 0
	v_pk_mul_f32 v[0:1], v[0:1], v[198:199]
	v_pk_mul_f32 v[2:3], v[2:3], v[200:201]
	v_pk_add_f32 v[4:5], v[212:213], 1.0 op_sel_hi:[1,0]
	v_pk_add_f32 v[6:7], v[210:211], 1.0 op_sel_hi:[1,0]
	v_pk_fma_f32 v[2:3], v[2:3], v[4:5], v[228:229]
	v_pk_fma_f32 v[0:1], v[0:1], v[6:7], v[226:227]
	s_nop 0
	v_cvt_pk_bf16_f32 v0, v0, v1
	v_cvt_pk_bf16_f32 v1, v2, v3
	global_store_dwordx2 v[30:31], v[0:1], off offset:1536
